# attention unit prologue: first wait moved to its first consumer (vmcnt(5): only K0 needed before QK0), plus GLU/in-proj permlane row-sum shuffles, on top of v23
# speedup vs baseline: 1.0085x; 1.0065x over previous
; __device__ __forceinline__ void attn_body(const bf16_t* __restrict__ Qb, const bf16_t* __restrict__ KVb, int hcol, bf16_t* __restrict__ Ob, float* __restrict__ rsqa, int seq, char* lds) {
;   int tid_ = threadIdx.x; asm volatile("" : "+v"(tid_));
;   const int tid = tid_, wid = __builtin_amdgcn_readfirstlane(tid >> 6), lane = tid & 63, r32 = lane & 31, hi = lane >> 5;
;   char* V_lds = lds; char* K_lds = lds + 2 * SHM_V;
;   float* ws = (float*)(lds + 2 * SHM_V + 3 * SHM_K) + wid * 64; float* li_l = ws; float* al_l = ws + 32;
;   float m_reg = -1e30f, l_reg = 0; f32x16 o[4] = {}; bf16x8 qr[8];
;   char* qlds = lds + 2 * SHM_V + 3 * SHM_K + NW * 64 * 4 + wid * 4096 + lane * 16;
;   int kb[4];
; #pragma unroll
;   for (int dl = 0; dl < 4; ++dl) kb[dl] = r32 * 384 + ((dl * 32 + hi * 16) ^ (((r32 >> 1) & 7) << 4));
;   const bf16_t* Qw = Qb + (long)(wid * QBLK + r32) * LDQ + hi * 8;
; #pragma unroll
;   for (int d0 = 0; d0 < 8; ++d0) qr[d0] = *reinterpret_cast<const bf16x8*>(Qw + d0 * 16);
; #pragma unroll
;   for (int d0 = 8; d0 < 12; ++d0) *reinterpret_cast<bf16x8*>(qlds + (d0 - 8) * 1024) = *reinterpret_cast<const bf16x8*>(Qw + d0 * 16);
;   DmaCtx dc; dc.wid = wid; dc.srd = __builtin_amdgcn_make_buffer_rsrc((void*)KVb, (short)0, 0x7fffffff, 0x00020000);
; #pragma unroll
;   for (int i = 0; i < 3; ++i) { const int b = (wid + 8 * i) * 1024 + lane * 16, row = b / 384, x = b % 384, blk = x >> 7, ch = ((x & 127) >> 4) ^ ((row >> 1) & 7), col = blk * 64 + ch * 8;
;     dc.koff[i] = (unsigned)(row * LDKV + (col < 128 ? hcol + col : 2048 + (col - 128))) * 2u; }
; #pragma unroll
;   for (int i = 0; i < 2; ++i) { const int b = (wid + 8 * i) * 1024 + lane * 16, st_ = b >> 9, kk = (st_ >> 2) * 8 + ((b & 511) >> 6), c = (st_ & 3) * 32 + ((b & 63) >> 1);
;     const int k = (kk & ~0xC) | ((kk & 4) << 1) | ((kk & 8) >> 1);
;     dc.voff[i] = (unsigned)(k * LDKV + hcol + 128 + c) * 2u; }
;   const __attribute__((address_space(3))) char* vb0 = (const __attribute__((address_space(3))) char*)V_lds + v_rd_base(lane);
;   constexpr size_t TILEB = (size_t)KVBLK * LDKV * 2;
;     ...
;   f32x16 pA0, pA1, pB0, pB1; float alA, alB; bf16x8 pa0, pa1, pa2, pa3; SMState st; const int NT = seq / KVBLK;
;   DMAK(0, 0); DMAV(0, 0); DMAK(1, 1);
;   asm volatile("s_waitcnt vmcnt(3)" ::: "memory"); BAR();
.LBB0_654:
	s_lshl_b32 s36, s0, 8
	s_add_i32 s8, s6, s36
	s_ashr_i32 s9, s8, 31
	s_mul_i32 s1, s8, 0xc00
	s_mul_hi_i32 s0, s8, 0xc00
	s_add_u32 s4, s3, s1
	s_addc_u32 s5, s21, s0
	s_ashr_i32 s7, s6, 31
	s_mul_i32 s1, s6, 0x1080
	v_mov_b32_e32 v72, v168
	s_mul_hi_i32 s0, s6, 0x1080
	s_add_u32 s28, s20, s1
	s_addc_u32 s10, s87, s0
	v_readfirstlane_b32 s1, v72
	s_ashr_i32 s11, s1, 6
	v_and_b32_e32 v187, 31, v72
	s_lshl_b32 s0, s11, 5
	v_bfe_u32 v186, v72, 5, 1
	v_or_b32_e32 v2, s0, v187
	v_mov_b64_e32 v[0:1], s[4:5]
	v_lshlrev_b32_e32 v166, 4, v186
	v_mad_i64_i32 v[0:1], s[4:5], v2, s42, v[0:1]
	v_lshl_add_u64 v[16:17], v[0:1], 0, v[166:167]
	global_load_dwordx4 v[0:3], v[16:17], off offset:256
	global_load_dwordx4 v[4:7], v[16:17], off offset:288
	global_load_dwordx4 v[8:11], v[16:17], off offset:320
	global_load_dwordx4 v[12:15], v[16:17], off offset:352
	global_load_dwordx4 v[156:159], v[16:17], off
	global_load_dwordx4 v[152:155], v[16:17], off offset:32
	global_load_dwordx4 v[148:151], v[16:17], off offset:64
	global_load_dwordx4 v[144:147], v[16:17], off offset:96
	global_load_dwordx4 v[140:143], v[16:17], off offset:128
	global_load_dwordx4 v[136:139], v[16:17], off offset:160
	global_load_dwordx4 v[132:135], v[16:17], off offset:192
	global_load_dwordx4 v[128:131], v[16:17], off offset:224
	v_and_b32_e32 v96, 63, v72
	v_lshlrev_b32_e32 v18, 3, v72
	v_lshlrev_b32_e32 v73, 4, v96
	s_lshl_b32 s69, s11, 10
	v_and_b32_e32 v57, 0x70, v18
	s_lshl_b32 s4, s11, 12
	v_or_b32_e32 v18, s69, v73
	s_add_i32 s4, s4, 0
	v_mul_hi_i32 v19, v18, s43
	v_add_u32_e32 v20, 0x2000, v18
	s_add_i32 s4, s4, 0x1a800
	v_add_u32_e32 v21, 0x4000, v18
	v_lshrrev_b32_e32 v22, 31, v19
	v_ashrrev_i32_e32 v19, 6, v19
	v_mul_hi_i32 v23, v20, s43
	v_add_u32_e32 v192, s4, v73
	v_mul_hi_i32 v24, v21, s43
	v_add_u32_e32 v16, v19, v22
	v_lshrrev_b32_e32 v17, 31, v23
	v_ashrrev_i32_e32 v19, 6, v23
	v_lshrrev_b32_e32 v22, 31, v24
	v_mul_i32_i24_e32 v23, 0x180, v16
	v_add_u32_e32 v17, v19, v17
	v_sub_u32_e32 v18, v18, v23
	v_mul_i32_i24_e32 v19, 0x180, v17
	v_lshrrev_b32_e32 v25, 1, v16
	v_lshrrev_b32_e32 v26, 4, v18
	v_sub_u32_e32 v19, v20, v19
	v_lshrrev_b32_e32 v23, 1, v17
	v_ashrrev_i32_e32 v18, 1, v18
	v_xor_b32_e32 v20, v26, v25
	v_lshrrev_b32_e32 v25, 4, v19
	v_and_b32_e32 v18, 0xffffffc0, v18
	v_ashrrev_i32_e32 v19, 1, v19
	v_lshlrev_b32_e32 v20, 3, v20
	v_xor_b32_e32 v23, v25, v23
	v_and_b32_e32 v19, 0xffffffc0, v19
	v_and_or_b32 v18, v20, 56, v18
	v_lshlrev_b32_e32 v20, 3, v23
	v_cmp_gt_i32_e32 vcc, s40, v18
	v_mad_i32_i24 v16, v16, s44, v18
	v_and_or_b32 v18, v20, 56, v19
	v_cndmask_b32_e32 v23, v161, v163, vcc
	v_cmp_gt_i32_e32 vcc, s40, v18
	s_and_b32 s4, s1, 64
	v_add_lshl_u32 v194, v16, v23, 1
	v_cndmask_b32_e32 v16, v161, v163, vcc
	s_and_b32 s29, s10, 0xffff
	s_add_i32 s70, s69, 0
	v_mad_i32_i24 v17, v17, s44, v18
	v_lshlrev_b32_e32 v74, 3, v96
	s_add_i32 m0, s70, 0x8000
	v_add_lshl_u32 v195, v17, v16, 1
	v_and_b32_e32 v75, 24, v74
	s_add_i32 s71, s70, 0x2000
	v_mul_u32_u24_e32 v56, 0x180, v187
	v_bitop3_b32 v193, v166, v56, v57 bitop3:0xde
	v_add_u32_e32 v68, 0, v193
	v_or_b32_e32 v48, 64, v166
	v_bitop3_b32 v200, v48, v56, v57 bitop3:0xde
	v_add_u32_e32 v70, 0, v200
	v_or_b32_e32 v58, 0x60, v166
	v_bitop3_b32 v201, v58, v56, v57 bitop3:0xde
	v_add_u32_e32 v71, 0, v201
	s_waitcnt vmcnt(11)
	ds_write_b128 v192, v[0:3]
	s_waitcnt vmcnt(10)
	ds_write_b128 v192, v[4:7] offset:1024
	s_waitcnt vmcnt(9)
	ds_write_b128 v192, v[8:11] offset:2048
	s_waitcnt vmcnt(8)
	ds_write_b128 v192, v[12:15] offset:3072
	v_ashrrev_i32_e32 v0, 6, v24
	v_add_u32_e32 v0, v0, v22
	v_mul_i32_i24_e32 v1, 0x180, v0
	v_sub_u32_e32 v1, v21, v1
	v_lshrrev_b32_e32 v2, 4, v1
	v_lshrrev_b32_e32 v3, 1, v0
	v_xor_b32_e32 v2, v2, v3
	v_ashrrev_i32_e32 v1, 1, v1
	v_and_b32_e32 v1, 0xffffffc0, v1
	v_lshlrev_b32_e32 v2, 3, v2
	v_and_or_b32 v1, v2, 56, v1
	v_cmp_gt_i32_e32 vcc, s40, v1
	v_mad_i32_i24 v0, v0, s44, v1
	v_bitop3_b32 v1, s4, v165, v96 bitop3:0xc8
	s_ashr_i32 s4, s69, 8
	v_cndmask_b32_e32 v2, v161, v163, vcc
	s_and_b32 s5, s4, 0x3fffff0
	s_lshr_b32 s4, s4, 1
	v_add_lshl_u32 v196, v0, v2, 1
	v_bfe_u32 v0, v72, 2, 2
	v_lshrrev_b32_e32 v2, 1, v72
	s_and_b32 s4, s4, 4
	v_and_or_b32 v0, v2, 8, v0
	s_or_b32 s4, s5, s4
	v_or_b32_e32 v2, s4, v0
	s_add_i32 s4, s69, 0x2000
	s_ashr_i32 s5, s4, 8
	s_and_b32 s10, s5, 0x3fffff0
	s_lshr_b32 s5, s5, 1
	s_and_b32 s5, s5, 4
	s_or_b32 s5, s10, s5
	buffer_load_dwordx4 v194, s[28:31], 0 offen lds
	s_add_i32 m0, s70, 0xa000
	v_or3_b32 v1, v1, s41, v75
	v_mul_lo_u32 v2, v2, s44
	v_or_b32_e32 v0, s5, v0
	buffer_load_dwordx4 v195, s[28:31], 0 offen lds
	s_add_i32 m0, s70, 0xc000
	v_add_lshl_u32 v197, v1, v2, 1
	v_mul_lo_u32 v0, v0, s44
	buffer_load_dwordx4 v196, s[28:31], 0 offen lds
	s_mov_b32 m0, s70
	v_add_lshl_u32 v198, v0, v1, 1
	buffer_load_dwordx4 v197, s[28:31], 0 offen lds
	s_mov_b32 m0, s71
	s_add_i32 s5, s69, s45
	buffer_load_dwordx4 v198, s[28:31], 0 offen lds
	s_add_i32 m0, s70, 0xe000
	v_or_b32_e32 v8, 32, v166
	buffer_load_dwordx4 v194, s[28:31], s66 offen lds
	s_add_i32 m0, s45, s4
	v_bitop3_b32 v199, v8, v56, v57 bitop3:0xde
	buffer_load_dwordx4 v195, s[28:31], s66 offen lds
	s_add_i32 m0, s5, 0x4000
	v_add_u32_e32 v69, 0, v199
	buffer_load_dwordx4 v196, s[28:31], s66 offen lds
	s_waitcnt vmcnt(5)
	s_waitcnt lgkmcnt(0)
	s_barrier
; #define BAR() do { asm volatile("s_waitcnt lgkmcnt(0)" ::: "memory"); __builtin_amdgcn_s_barrier(); asm volatile("" ::: "memory"); } while (0)
; __device__ __forceinline__ void qkt(f32x16& p0, f32x16& p1, const char* Ks, const bf16x8* qr, const char* qlds, const int* kb) {
;   p0 = f32x16{}; p1 = f32x16{};
; #pragma unroll
;   for (int d0 = 0; d0 < 12; ++d0) { const int off = kb[d0 & 3] + (d0 >> 2) * 128;
;     bf16x8 b0 = *reinterpret_cast<const bf16x8*>(Ks + off);
;     bf16x8 b1 = *reinterpret_cast<const bf16x8*>(Ks + off + 32 * 384);
;     bf16x8 q; if (d0 < 8) q = qr[d0]; else q = *reinterpret_cast<const bf16x8*>(qlds + (d0 - 8) * 1024);
;     p0 = __builtin_amdgcn_mfma_f32_32x32x16_bf16(b0, q, p0, 0, 0, 0);
;     p1 = __builtin_amdgcn_mfma_f32_32x32x16_bf16(b1, q, p1, 0, 0, 0); }
; }
; __device__ __forceinline__ void attn_body(const bf16_t* __restrict__ Qb, const bf16_t* __restrict__ KVb, int hcol, bf16_t* __restrict__ Ob, float* __restrict__ rsqa, int seq, char* lds) {
;     ...
;   qkt(pA0, pA1, K_lds, qr, qlds, kb); partialSM0(pA0, pA1, m_reg); alA = 1.f;
;   asm volatile("s_waitcnt vmcnt(0)" ::: "memory"); BAR();
	ds_read_b128 v[0:3], v68 offset:32768
	ds_read_b128 v[4:7], v68 offset:32896
	s_waitcnt vmcnt(15) lgkmcnt(1)
	v_mfma_f32_32x32x16_bf16 v[16:31], v[0:3], v[156:159], 0
	ds_read_b128 v[0:3], v68 offset:45056
	ds_read_b128 v[8:11], v68 offset:33024
	s_and_b32 s1, s1, 0x3fffffc0
	s_mov_b32 s49, s48
	s_lshl_b32 s1, s1, 2
	s_mov_b32 s50, s48
	s_mov_b32 s51, s48
	s_waitcnt lgkmcnt(1)
	v_mfma_f32_32x32x16_bf16 v[32:47], v[0:3], v[156:159], 0
	ds_read_b128 v[0:3], v69 offset:32768
	ds_read_b128 v[12:15], v69 offset:32896
	ds_read_b128 v[48:51], v69 offset:33024
	s_mov_b32 s52, s48
	s_mov_b32 s53, s48
	s_mov_b32 s54, s48
	s_mov_b32 s55, s48
	s_mov_b32 s56, s48
	s_waitcnt vmcnt(14) lgkmcnt(2)
	v_mfma_f32_32x32x16_bf16 v[16:31], v[0:3], v[152:155], v[16:31]
	ds_read_b128 v[0:3], v69 offset:45056
	s_mov_b32 s57, s48
	s_mov_b32 s58, s48
	s_mov_b32 s59, s48
	s_mov_b32 s60, s48
	s_mov_b32 s61, s48
	s_mov_b32 s62, s48
	s_waitcnt lgkmcnt(0)
	v_mfma_f32_32x32x16_bf16 v[32:47], v[0:3], v[152:155], v[32:47]
	ds_read_b128 v[0:3], v70 offset:32768
	ds_read_b128 v[52:55], v70 offset:32896
	ds_read_b128 v[56:59], v70 offset:33024
	s_mov_b32 s63, s48
	s_add_i32 s1, s1, 0
	s_add_i32 s1, s1, 0x1a000
	s_mov_b32 s72, 2
	s_mov_b32 s73, 1
	s_waitcnt vmcnt(13) lgkmcnt(2)
	v_mfma_f32_32x32x16_bf16 v[16:31], v[0:3], v[148:151], v[16:31]
	ds_read_b128 v[0:3], v70 offset:45056
	v_cmp_gt_u32_e64 s[4:5], 32, v96
	v_lshl_add_u32 v189, v187, 2, s1
	v_mov_b32_e32 v202, 1.0
	v_mov_b32_e32 v190, 0
	s_waitcnt lgkmcnt(0)
	v_mfma_f32_32x32x16_bf16 v[32:47], v[0:3], v[148:151], v[32:47]
	ds_read_b128 v[0:3], v71 offset:32768
	ds_read_b128 v[60:63], v71 offset:32896
	s_waitcnt vmcnt(12) lgkmcnt(1)
	v_mfma_f32_32x32x16_bf16 v[16:31], v[0:3], v[144:147], v[16:31]
	ds_read_b128 v[0:3], v71 offset:45056
	ds_read_b128 v[64:67], v71 offset:33024
	s_waitcnt lgkmcnt(1)
	v_mfma_f32_32x32x16_bf16 v[32:47], v[0:3], v[144:147], v[32:47]
	s_waitcnt vmcnt(11)
	v_mfma_f32_32x32x16_bf16 v[16:31], v[4:7], v[140:143], v[16:31]
	ds_read_b128 v[0:3], v68 offset:45184
	ds_read_b128 v[4:7], v68 offset:45312
	s_waitcnt lgkmcnt(1)
	v_mfma_f32_32x32x16_bf16 v[32:47], v[0:3], v[140:143], v[32:47]
	s_waitcnt vmcnt(10)
	v_mfma_f32_32x32x16_bf16 v[16:31], v[12:15], v[136:139], v[16:31]
	ds_read_b128 v[0:3], v69 offset:45184
	ds_read_b128 v[12:15], v69 offset:45312
	s_waitcnt lgkmcnt(1)
	v_mfma_f32_32x32x16_bf16 v[32:47], v[0:3], v[136:139], v[32:47]
	s_waitcnt vmcnt(9)
	v_mfma_f32_32x32x16_bf16 v[16:31], v[52:55], v[132:135], v[16:31]
	ds_read_b128 v[0:3], v70 offset:45184
	ds_read_b128 v[52:55], v70 offset:45312
	s_waitcnt lgkmcnt(1)
	v_mfma_f32_32x32x16_bf16 v[32:47], v[0:3], v[132:135], v[32:47]
	s_waitcnt vmcnt(8)
	v_mfma_f32_32x32x16_bf16 v[16:31], v[60:63], v[128:131], v[16:31]
	ds_read_b128 v[0:3], v71 offset:45184
	ds_read_b128 v[60:63], v71 offset:45312
	s_waitcnt lgkmcnt(1)
	v_mfma_f32_32x32x16_bf16 v[32:47], v[0:3], v[128:131], v[32:47]
	ds_read_b128 v[0:3], v192
	ds_read_b128 v[68:71], v192 offset:1024
	s_waitcnt lgkmcnt(1)
	v_mfma_f32_32x32x16_bf16 v[16:31], v[8:11], v[0:3], v[16:31]
	v_mfma_f32_32x32x16_bf16 v[32:47], v[4:7], v[0:3], v[32:47]
	ds_read_b128 v[0:3], v192 offset:2048
	v_lshlrev_b32_e32 v5, 1, v72
	v_and_b32_e32 v4, 0xc0, v73
	v_and_b32_e32 v6, 0x100, v74
	v_add3_u32 v4, 0, v75, v4
	v_and_b32_e32 v5, 32, v5
	v_add3_u32 v188, v4, v5, v6
	s_waitcnt lgkmcnt(1)
	v_mfma_f32_32x32x16_bf16 v[16:31], v[48:51], v[68:71], v[16:31]
	ds_read_b128 v[48:51], v192 offset:3072
	s_waitcnt vmcnt(0)
	s_waitcnt lgkmcnt(0)
	s_barrier
; __device__ __forceinline__ void partialSM0(f32x16& p0, f32x16& p1, float& M) {
;   float pmax = p0[0];
; #pragma unroll
;   for (int r = 1; r < 16; ++r) pmax = fmaxf(pmax, p0[r]);
; #pragma unroll
;   for (int r = 0; r < 16; ++r) pmax = fmaxf(pmax, p1[r]);
;   { auto rr = __builtin_amdgcn_permlane32_swap(__float_as_uint(pmax), __float_as_uint(pmax), false, false);
;     pmax = fmaxf(__uint_as_float(rr[0]), __uint_as_float(rr[1])); }
;   M = pmax;
; #pragma unroll
;   for (int r = 0; r < 16; ++r) { p0[r] -= pmax; p1[r] -= pmax; }
; #pragma unroll
;   for (int r = 0; r < 16; ++r) p0[r] = __builtin_amdgcn_exp2f(p0[r]);
; }
	v_mfma_f32_32x32x16_bf16 v[32:47], v[12:15], v[68:71], v[32:47]
	s_waitcnt lgkmcnt(1)
	v_mfma_f32_32x32x16_bf16 v[16:31], v[56:59], v[0:3], v[16:31]
	v_mfma_f32_32x32x16_bf16 v[32:47], v[52:55], v[0:3], v[32:47]
	v_mov_b64_e32 v[0:1], s[48:49]
	v_mov_b64_e32 v[14:15], s[62:63]
	v_mov_b64_e32 v[2:3], s[50:51]
	v_mov_b64_e32 v[4:5], s[52:53]
	v_mov_b64_e32 v[6:7], s[54:55]
	v_mov_b64_e32 v[8:9], s[56:57]
	v_mov_b64_e32 v[10:11], s[58:59]
	s_waitcnt lgkmcnt(0)
	v_mfma_f32_32x32x16_bf16 v[16:31], v[64:67], v[48:51], v[16:31]
	v_mov_b64_e32 v[12:13], s[60:61]
	s_add_i32 s50, s70, 0x4000
	s_add_i32 s49, s70, 0x6000
	s_mov_b32 s51, 0x84000
	v_mfma_f32_32x32x16_bf16 v[32:47], v[60:63], v[48:51], v[32:47]
	s_nop 6
	v_max_f32_e32 v48, v17, v17
	v_max_f32_e32 v49, v16, v16
	v_max_f32_e32 v48, v49, v48
	v_max3_f32 v48, v48, v18, v19
	v_max3_f32 v48, v48, v20, v21
	v_max3_f32 v48, v48, v22, v23
	v_max3_f32 v48, v48, v24, v25
	v_max3_f32 v48, v48, v26, v27
	v_max3_f32 v48, v48, v28, v29
	v_max3_f32 v48, v48, v30, v31
	v_max3_f32 v48, v48, v32, v33
	v_max3_f32 v48, v48, v34, v35
	v_max3_f32 v48, v48, v36, v37
	v_max3_f32 v48, v48, v38, v39
	v_max3_f32 v48, v48, v40, v41
	v_max3_f32 v48, v48, v42, v43
	v_max3_f32 v48, v48, v44, v45
	v_max3_f32 v48, v48, v46, v47
	v_mov_b32_e32 v49, v48
	s_nop 1
	v_permlane32_swap_b32_e32 v48, v49
	v_max_f32_e32 v49, v49, v49
	v_max_f32_e32 v48, v48, v48
	v_max_f32_e32 v191, v48, v49
	v_sub_f32_e32 v16, v16, v191
	v_exp_f32_e32 v64, v16
	v_sub_f32_e32 v16, v17, v191
	v_exp_f32_e32 v65, v16
	v_sub_f32_e32 v16, v18, v191
	v_exp_f32_e32 v66, v16
	v_sub_f32_e32 v16, v19, v191
	v_exp_f32_e32 v67, v16
	v_sub_f32_e32 v16, v20, v191
	v_exp_f32_e32 v68, v16
	v_sub_f32_e32 v16, v21, v191
	v_exp_f32_e32 v69, v16
	v_sub_f32_e32 v16, v22, v191
	v_exp_f32_e32 v70, v16
	v_sub_f32_e32 v16, v23, v191
	v_exp_f32_e32 v71, v16
	v_sub_f32_e32 v16, v24, v191
	v_exp_f32_e32 v72, v16
	v_sub_f32_e32 v16, v25, v191
	v_exp_f32_e32 v73, v16
	v_sub_f32_e32 v16, v26, v191
	v_exp_f32_e32 v74, v16
	v_sub_f32_e32 v16, v27, v191
	v_exp_f32_e32 v75, v16
	v_sub_f32_e32 v16, v28, v191
	v_exp_f32_e32 v76, v16
	v_sub_f32_e32 v16, v29, v191
	v_exp_f32_e32 v77, v16
	v_sub_f32_e32 v16, v30, v191
	v_exp_f32_e32 v78, v16
	v_sub_f32_e32 v16, v31, v191
	v_exp_f32_e32 v79, v16
	v_sub_f32_e32 v95, v47, v191
	v_sub_f32_e32 v94, v46, v191
	v_sub_f32_e32 v93, v45, v191
	v_sub_f32_e32 v92, v44, v191
	v_sub_f32_e32 v91, v43, v191
	v_sub_f32_e32 v90, v42, v191
	v_sub_f32_e32 v89, v41, v191
	v_sub_f32_e32 v88, v40, v191
	v_sub_f32_e32 v87, v39, v191
	v_sub_f32_e32 v86, v38, v191
	v_sub_f32_e32 v85, v37, v191
	v_sub_f32_e32 v84, v36, v191
	v_sub_f32_e32 v83, v35, v191
	v_sub_f32_e32 v82, v34, v191
	v_sub_f32_e32 v81, v33, v191
	v_sub_f32_e32 v80, v32, v191
	v_mov_b64_e32 v[62:63], v[14:15]
	v_mov_b64_e32 v[46:47], v[14:15]
	v_mov_b64_e32 v[30:31], v[14:15]
	v_mov_b64_e32 v[60:61], v[12:13]
	v_mov_b64_e32 v[58:59], v[10:11]
	v_mov_b64_e32 v[56:57], v[8:9]
	v_mov_b64_e32 v[54:55], v[6:7]
	v_mov_b64_e32 v[52:53], v[4:5]
	v_mov_b64_e32 v[50:51], v[2:3]
	v_mov_b64_e32 v[48:49], v[0:1]
	v_mov_b64_e32 v[44:45], v[12:13]
	v_mov_b64_e32 v[42:43], v[10:11]
	v_mov_b64_e32 v[40:41], v[8:9]
	v_mov_b64_e32 v[38:39], v[6:7]
	v_mov_b64_e32 v[36:37], v[4:5]
	v_mov_b64_e32 v[34:35], v[2:3]
	v_mov_b64_e32 v[32:33], v[0:1]
	v_mov_b64_e32 v[28:29], v[12:13]
	v_mov_b64_e32 v[26:27], v[10:11]
	v_mov_b64_e32 v[24:25], v[8:9]
	v_mov_b64_e32 v[22:23], v[6:7]
	v_mov_b64_e32 v[20:21], v[4:5]
	v_mov_b64_e32 v[18:19], v[2:3]
	v_mov_b64_e32 v[16:17], v[0:1]
